# mLSTM: L2 warm-up VGPR loads removed (LDS-DMA fetches straight from memory)
# baseline (speedup 1.0000x reference)
; __device__ __forceinline__ void mlstm_item(const Args& a, LAS unsigned char* L, bool sample, int b, int hh, int sl, bool dry = false) {
;     ...
;         if (c + 1 < nchunks) PREFETCH(c + 1);
.LBB0_665:
	s_or_b64 exec, exec, s[72:73]
	v_lshl_add_u64 v[8:9], v[74:75], 0, s[70:71]
	v_add_co_u32_e32 v0, vcc, 0x72000, v8
	s_nop 1
	v_addc_co_u32_e32 v1, vcc, 0, v9, vcc
	v_add_co_u32_e32 v8, vcc, 0xaa000, v8
	s_nop 0
	v_addc_co_u32_e32 v9, vcc, 0, v9, vcc
	s_nop 0
	s_and_saveexec_b64 s[72:73], s[0:1]
	s_cbranch_execz .LBB0_667
	v_lshl_add_u64 v[56:57], v[72:73], 0, s[70:71]
	v_add_co_u32_e32 v58, vcc, 0x73000, v56
	s_nop 1
	v_addc_co_u32_e32 v59, vcc, 0, v57, vcc
	v_add_co_u32_e32 v56, vcc, 0x76000, v56
	s_nop 1
	v_addc_co_u32_e32 v57, vcc, 0, v57, vcc
	global_load_dwordx2 v[62:63], v[58:59], off
	global_load_dwordx2 v[64:65], v[56:57], off offset:2048
